# the seven GEMM K-loop head labels aligned to 64 bytes (.p2align 6)
# speedup vs baseline: 1.0095x; 1.0095x over previous
.LBB0_244:
	s_ashr_i32 s43, s42, 2
	s_and_b64 s[10:11], s[12:13], exec
	s_cselect_b32 s10, s43, s15
	s_ashr_i32 s11, s10, 31
	s_lshl_b64 s[10:11], s[10:11], 18
	s_add_u32 s10, s26, s10
	s_addc_u32 s11, s27, s11
	s_and_b64 s[20:21], s[12:13], exec
	s_cselect_b32 s15, s11, s19
	s_cselect_b32 s45, s10, s18
	s_add_u32 s46, s18, 0x100
	v_mov_b32_e32 v2, 0
	s_addc_u32 s47, s19, 0
	s_mov_b32 s52, -2
	v_mov_b32_e32 v3, v2
	v_mov_b32_e32 v4, v2
	v_mov_b32_e32 v5, v2
	v_mov_b32_e32 v6, v2
	v_mov_b32_e32 v7, v2
	v_mov_b32_e32 v8, v2
	v_mov_b32_e32 v9, v2
	v_mov_b32_e32 v10, v2
	v_mov_b32_e32 v11, v2
	v_mov_b32_e32 v12, v2
	v_mov_b32_e32 v13, v2
	v_mov_b32_e32 v14, v2
	v_mov_b32_e32 v15, v2
	v_mov_b32_e32 v16, v2
	v_mov_b32_e32 v17, v2
	v_mov_b32_e32 v18, v2
	v_mov_b32_e32 v19, v2
	v_mov_b32_e32 v20, v2
	v_mov_b32_e32 v21, v2
	v_mov_b32_e32 v22, v2
	v_mov_b32_e32 v23, v2
	v_mov_b32_e32 v24, v2
	v_mov_b32_e32 v25, v2
	v_mov_b32_e32 v26, v2
	v_mov_b32_e32 v27, v2
	v_mov_b32_e32 v28, v2
	v_mov_b32_e32 v29, v2
	v_mov_b32_e32 v30, v2
	v_mov_b32_e32 v31, v2
	v_mov_b32_e32 v32, v2
	v_mov_b32_e32 v33, v2
	v_mov_b32_e32 v34, v2
	v_mov_b32_e32 v35, v2
	v_mov_b32_e32 v36, v2
	v_mov_b32_e32 v37, v2
	v_mov_b32_e32 v38, v2
	v_mov_b32_e32 v39, v2
	v_mov_b32_e32 v40, v2
	v_mov_b32_e32 v41, v2
	v_mov_b32_e32 v42, v2
	v_mov_b32_e32 v43, v2
	v_mov_b32_e32 v44, v2
	v_mov_b32_e32 v45, v2
	v_mov_b32_e32 v46, v2
	v_mov_b32_e32 v47, v2
	v_mov_b32_e32 v48, v2
	v_mov_b32_e32 v49, v2
	v_mov_b32_e32 v50, v2
	v_mov_b32_e32 v51, v2
	v_mov_b32_e32 v52, v2
	v_mov_b32_e32 v53, v2
	v_mov_b32_e32 v54, v2
	v_mov_b32_e32 v55, v2
	v_mov_b32_e32 v56, v2
	v_mov_b32_e32 v57, v2
	v_mov_b32_e32 v58, v2
	v_mov_b32_e32 v59, v2
	v_mov_b32_e32 v60, v2
	v_mov_b32_e32 v61, v2
	v_mov_b32_e32 v62, v2
	v_mov_b32_e32 v63, v2
	v_mov_b32_e32 v64, v2
	v_mov_b32_e32 v65, v2
	.p2align	6

.LBB0_406:
	s_add_u32 s3, s18, 0x100
	v_mov_b32_e32 v2, 0
	s_addc_u32 s45, s19, 0
	s_mov_b32 s46, -2
	v_mov_b32_e32 v3, v2
	v_mov_b32_e32 v4, v2
	v_mov_b32_e32 v5, v2
	v_mov_b32_e32 v6, v2
	v_mov_b32_e32 v7, v2
	v_mov_b32_e32 v8, v2
	v_mov_b32_e32 v9, v2
	v_mov_b32_e32 v18, v2
	v_mov_b32_e32 v19, v2
	v_mov_b32_e32 v20, v2
	v_mov_b32_e32 v21, v2
	v_mov_b32_e32 v22, v2
	v_mov_b32_e32 v23, v2
	v_mov_b32_e32 v24, v2
	v_mov_b32_e32 v25, v2
	v_mov_b32_e32 v42, v2
	v_mov_b32_e32 v43, v2
	v_mov_b32_e32 v44, v2
	v_mov_b32_e32 v45, v2
	v_mov_b32_e32 v46, v2
	v_mov_b32_e32 v47, v2
	v_mov_b32_e32 v48, v2
	v_mov_b32_e32 v49, v2
	v_mov_b32_e32 v58, v2
	v_mov_b32_e32 v59, v2
	v_mov_b32_e32 v60, v2
	v_mov_b32_e32 v61, v2
	v_mov_b32_e32 v62, v2
	v_mov_b32_e32 v63, v2
	v_mov_b32_e32 v64, v2
	v_mov_b32_e32 v65, v2
	v_mov_b32_e32 v10, v2
	v_mov_b32_e32 v11, v2
	v_mov_b32_e32 v12, v2
	v_mov_b32_e32 v13, v2
	v_mov_b32_e32 v14, v2
	v_mov_b32_e32 v15, v2
	v_mov_b32_e32 v16, v2
	v_mov_b32_e32 v17, v2
	v_mov_b32_e32 v26, v2
	v_mov_b32_e32 v27, v2
	v_mov_b32_e32 v28, v2
	v_mov_b32_e32 v29, v2
	v_mov_b32_e32 v30, v2
	v_mov_b32_e32 v31, v2
	v_mov_b32_e32 v32, v2
	v_mov_b32_e32 v33, v2
	v_mov_b32_e32 v50, v2
	v_mov_b32_e32 v51, v2
	v_mov_b32_e32 v52, v2
	v_mov_b32_e32 v53, v2
	v_mov_b32_e32 v54, v2
	v_mov_b32_e32 v55, v2
	v_mov_b32_e32 v56, v2
	v_mov_b32_e32 v57, v2
	v_mov_b32_e32 v66, v2
	v_mov_b32_e32 v67, v2
	v_mov_b32_e32 v68, v2
	v_mov_b32_e32 v69, v2
	v_mov_b32_e32 v70, v2
	v_mov_b32_e32 v71, v2
	v_mov_b32_e32 v72, v2
	v_mov_b32_e32 v73, v2
	v_mov_b32_e32 v74, v2
	v_mov_b32_e32 v75, v2
	v_mov_b32_e32 v76, v2
	v_mov_b32_e32 v77, v2
	v_mov_b32_e32 v78, v2
	v_mov_b32_e32 v79, v2
	v_mov_b32_e32 v80, v2
	v_mov_b32_e32 v81, v2
	v_mov_b32_e32 v90, v2
	v_mov_b32_e32 v91, v2
	v_mov_b32_e32 v92, v2
	v_mov_b32_e32 v93, v2
	v_mov_b32_e32 v94, v2
	v_mov_b32_e32 v95, v2
	v_mov_b32_e32 v96, v2
	v_mov_b32_e32 v97, v2
	v_mov_b32_e32 v110, v2
	v_mov_b32_e32 v111, v2
	v_mov_b32_e32 v112, v2
	v_mov_b32_e32 v113, v2
	v_mov_b32_e32 v114, v2
	v_mov_b32_e32 v115, v2
	v_mov_b32_e32 v116, v2
	v_mov_b32_e32 v117, v2
	v_mov_b32_e32 v134, v2
	v_mov_b32_e32 v135, v2
	v_mov_b32_e32 v136, v2
	v_mov_b32_e32 v137, v2
	v_mov_b32_e32 v138, v2
	v_mov_b32_e32 v139, v2
	v_mov_b32_e32 v140, v2
	v_mov_b32_e32 v141, v2
	v_mov_b32_e32 v82, v2
	v_mov_b32_e32 v83, v2
	v_mov_b32_e32 v84, v2
	v_mov_b32_e32 v85, v2
	v_mov_b32_e32 v86, v2
	v_mov_b32_e32 v87, v2
	v_mov_b32_e32 v88, v2
	v_mov_b32_e32 v89, v2
	v_mov_b32_e32 v98, v2
	v_mov_b32_e32 v99, v2
	v_mov_b32_e32 v100, v2
	v_mov_b32_e32 v101, v2
	v_mov_b32_e32 v102, v2
	v_mov_b32_e32 v103, v2
	v_mov_b32_e32 v104, v2
	v_mov_b32_e32 v105, v2
	v_mov_b32_e32 v122, v2
	v_mov_b32_e32 v123, v2
	v_mov_b32_e32 v124, v2
	v_mov_b32_e32 v125, v2
	v_mov_b32_e32 v126, v2
	v_mov_b32_e32 v127, v2
	v_mov_b32_e32 v128, v2
	v_mov_b32_e32 v129, v2
	v_mov_b32_e32 v150, v2
	v_mov_b32_e32 v151, v2
	v_mov_b32_e32 v152, v2
	v_mov_b32_e32 v153, v2
	v_mov_b32_e32 v158, v2
	v_mov_b32_e32 v159, v2
	v_mov_b32_e32 v160, v2
	v_mov_b32_e32 v161, v2
	.p2align	6

.LBB0_500:
	s_ashr_i32 s19, s18, 31
	s_lshl_b64 s[2:3], s[18:19], 19
	s_add_u32 s20, s38, s2
	s_addc_u32 s21, s39, s3
	s_and_b64 s[2:3], s[6:7], exec
	s_cselect_b32 s2, s21, s29
	s_cselect_b32 s3, s20, s28
	s_ashr_i32 s17, s16, 31
	s_lshl_b64 s[22:23], s[16:17], 19
	s_add_u32 s22, s40, s22
	s_addc_u32 s23, s41, s23
	s_and_b64 s[34:35], s[6:7], exec
	s_cselect_b32 s17, s23, s31
	s_cselect_b32 s19, s22, s30
	s_add_u32 s28, s28, 0x40080
	s_addc_u32 s29, s29, 0
	s_add_u32 s25, s30, 0x100
	v_mov_b32_e32 v2, 0
	s_addc_u32 s27, s31, 0
	s_mov_b32 s50, -2
	v_mov_b32_e32 v3, v2
	v_mov_b32_e32 v4, v2
	v_mov_b32_e32 v5, v2
	v_mov_b32_e32 v10, v2
	v_mov_b32_e32 v11, v2
	v_mov_b32_e32 v12, v2
	v_mov_b32_e32 v13, v2
	v_mov_b32_e32 v18, v2
	v_mov_b32_e32 v19, v2
	v_mov_b32_e32 v20, v2
	v_mov_b32_e32 v21, v2
	v_mov_b32_e32 v26, v2
	v_mov_b32_e32 v27, v2
	v_mov_b32_e32 v28, v2
	v_mov_b32_e32 v29, v2
	v_mov_b32_e32 v34, v2
	v_mov_b32_e32 v35, v2
	v_mov_b32_e32 v36, v2
	v_mov_b32_e32 v37, v2
	v_mov_b32_e32 v42, v2
	v_mov_b32_e32 v43, v2
	v_mov_b32_e32 v44, v2
	v_mov_b32_e32 v45, v2
	v_mov_b32_e32 v50, v2
	v_mov_b32_e32 v51, v2
	v_mov_b32_e32 v52, v2
	v_mov_b32_e32 v53, v2
	v_mov_b32_e32 v58, v2
	v_mov_b32_e32 v59, v2
	v_mov_b32_e32 v60, v2
	v_mov_b32_e32 v61, v2
	v_mov_b32_e32 v6, v2
	v_mov_b32_e32 v7, v2
	v_mov_b32_e32 v8, v2
	v_mov_b32_e32 v9, v2
	v_mov_b32_e32 v14, v2
	v_mov_b32_e32 v15, v2
	v_mov_b32_e32 v16, v2
	v_mov_b32_e32 v17, v2
	v_mov_b32_e32 v22, v2
	v_mov_b32_e32 v23, v2
	v_mov_b32_e32 v24, v2
	v_mov_b32_e32 v25, v2
	v_mov_b32_e32 v30, v2
	v_mov_b32_e32 v31, v2
	v_mov_b32_e32 v32, v2
	v_mov_b32_e32 v33, v2
	v_mov_b32_e32 v38, v2
	v_mov_b32_e32 v39, v2
	v_mov_b32_e32 v40, v2
	v_mov_b32_e32 v41, v2
	v_mov_b32_e32 v46, v2
	v_mov_b32_e32 v47, v2
	v_mov_b32_e32 v48, v2
	v_mov_b32_e32 v49, v2
	v_mov_b32_e32 v54, v2
	v_mov_b32_e32 v55, v2
	v_mov_b32_e32 v56, v2
	v_mov_b32_e32 v57, v2
	v_mov_b32_e32 v62, v2
	v_mov_b32_e32 v63, v2
	v_mov_b32_e32 v64, v2
	v_mov_b32_e32 v65, v2
	v_mov_b32_e32 v66, v2
	v_mov_b32_e32 v67, v2
	v_mov_b32_e32 v68, v2
	v_mov_b32_e32 v69, v2
	v_mov_b32_e32 v74, v2
	v_mov_b32_e32 v75, v2
	v_mov_b32_e32 v76, v2
	v_mov_b32_e32 v77, v2
	v_mov_b32_e32 v82, v2
	v_mov_b32_e32 v83, v2
	v_mov_b32_e32 v84, v2
	v_mov_b32_e32 v85, v2
	v_mov_b32_e32 v90, v2
	v_mov_b32_e32 v91, v2
	v_mov_b32_e32 v92, v2
	v_mov_b32_e32 v93, v2
	v_mov_b32_e32 v98, v2
	v_mov_b32_e32 v99, v2
	v_mov_b32_e32 v100, v2
	v_mov_b32_e32 v101, v2
	v_mov_b32_e32 v106, v2
	v_mov_b32_e32 v107, v2
	v_mov_b32_e32 v108, v2
	v_mov_b32_e32 v109, v2
	v_mov_b32_e32 v126, v2
	v_mov_b32_e32 v127, v2
	v_mov_b32_e32 v128, v2
	v_mov_b32_e32 v129, v2
	v_mov_b32_e32 v134, v2
	v_mov_b32_e32 v135, v2
	v_mov_b32_e32 v136, v2
	v_mov_b32_e32 v137, v2
	v_mov_b32_e32 v70, v2
	v_mov_b32_e32 v71, v2
	v_mov_b32_e32 v72, v2
	v_mov_b32_e32 v73, v2
	v_mov_b32_e32 v78, v2
	v_mov_b32_e32 v79, v2
	v_mov_b32_e32 v80, v2
	v_mov_b32_e32 v81, v2
	v_mov_b32_e32 v86, v2
	v_mov_b32_e32 v87, v2
	v_mov_b32_e32 v88, v2
	v_mov_b32_e32 v89, v2
	v_mov_b32_e32 v94, v2
	v_mov_b32_e32 v95, v2
	v_mov_b32_e32 v96, v2
	v_mov_b32_e32 v97, v2
	v_mov_b32_e32 v102, v2
	v_mov_b32_e32 v103, v2
	v_mov_b32_e32 v104, v2
	v_mov_b32_e32 v105, v2
	v_mov_b32_e32 v110, v2
	v_mov_b32_e32 v111, v2
	v_mov_b32_e32 v112, v2
	v_mov_b32_e32 v113, v2
	v_mov_b32_e32 v118, v2
	v_mov_b32_e32 v119, v2
	v_mov_b32_e32 v120, v2
	v_mov_b32_e32 v121, v2
	v_mov_b32_e32 v138, v2
	v_mov_b32_e32 v139, v2
	v_mov_b32_e32 v140, v2
	v_mov_b32_e32 v141, v2
	.p2align	6

.LBB0_612:
	s_ashr_i32 s29, s28, 31
	s_lshl_b64 s[2:3], s[28:29], 19
	s_add_u32 s30, s47, s2
	s_addc_u32 s31, s50, s3
	s_and_b64 s[2:3], s[6:7], exec
	s_cselect_b32 s2, s31, s9
	s_cselect_b32 s3, s30, s8
	s_ashr_i32 s27, s26, 31
	s_lshl_b64 s[34:35], s[26:27], 19
	s_add_u32 s34, s52, s34
	s_addc_u32 s35, s56, s35
	s_and_b64 s[40:41], s[6:7], exec
	s_cselect_b32 s11, s35, s39
	s_cselect_b32 s27, s34, s38
	s_add_u32 s8, s8, 0x40080
	s_addc_u32 s9, s9, 0
	s_add_u32 s29, s38, 0x100
	v_mov_b32_e32 v58, 0
	s_addc_u32 s42, s39, 0
	s_mov_b32 s43, -2
	v_mov_b32_e32 v59, v58
	v_mov_b32_e32 v60, v58
	v_mov_b32_e32 v61, v58
	v_mov_b32_e32 v62, v58
	v_mov_b32_e32 v63, v58
	v_mov_b32_e32 v64, v58
	v_mov_b32_e32 v65, v58
	v_mov_b32_e32 v74, v58
	v_mov_b32_e32 v75, v58
	v_mov_b32_e32 v76, v58
	v_mov_b32_e32 v77, v58
	v_mov_b32_e32 v78, v58
	v_mov_b32_e32 v79, v58
	v_mov_b32_e32 v80, v58
	v_mov_b32_e32 v81, v58
	v_mov_b32_e32 v82, v58
	v_mov_b32_e32 v83, v58
	v_mov_b32_e32 v84, v58
	v_mov_b32_e32 v85, v58
	v_mov_b32_e32 v86, v58
	v_mov_b32_e32 v87, v58
	v_mov_b32_e32 v88, v58
	v_mov_b32_e32 v89, v58
	v_mov_b32_e32 v90, v58
	v_mov_b32_e32 v91, v58
	v_mov_b32_e32 v92, v58
	v_mov_b32_e32 v93, v58
	v_mov_b32_e32 v94, v58
	v_mov_b32_e32 v95, v58
	v_mov_b32_e32 v96, v58
	v_mov_b32_e32 v97, v58
	v_mov_b32_e32 v2, v58
	v_mov_b32_e32 v3, v58
	v_mov_b32_e32 v4, v58
	v_mov_b32_e32 v5, v58
	v_mov_b32_e32 v6, v58
	v_mov_b32_e32 v7, v58
	v_mov_b32_e32 v8, v58
	v_mov_b32_e32 v9, v58
	v_mov_b32_e32 v10, v58
	v_mov_b32_e32 v11, v58
	v_mov_b32_e32 v12, v58
	v_mov_b32_e32 v13, v58
	v_mov_b32_e32 v14, v58
	v_mov_b32_e32 v15, v58
	v_mov_b32_e32 v16, v58
	v_mov_b32_e32 v17, v58
	v_mov_b32_e32 v18, v58
	v_mov_b32_e32 v19, v58
	v_mov_b32_e32 v20, v58
	v_mov_b32_e32 v21, v58
	v_mov_b32_e32 v22, v58
	v_mov_b32_e32 v23, v58
	v_mov_b32_e32 v24, v58
	v_mov_b32_e32 v25, v58
	v_mov_b32_e32 v26, v58
	v_mov_b32_e32 v27, v58
	v_mov_b32_e32 v28, v58
	v_mov_b32_e32 v29, v58
	v_mov_b32_e32 v30, v58
	v_mov_b32_e32 v31, v58
	v_mov_b32_e32 v32, v58
	v_mov_b32_e32 v33, v58
	v_mov_b32_e32 v98, v58
	v_mov_b32_e32 v99, v58
	v_mov_b32_e32 v100, v58
	v_mov_b32_e32 v101, v58
	v_mov_b32_e32 v102, v58
	v_mov_b32_e32 v103, v58
	v_mov_b32_e32 v104, v58
	v_mov_b32_e32 v105, v58
	v_mov_b32_e32 v122, v58
	v_mov_b32_e32 v123, v58
	v_mov_b32_e32 v124, v58
	v_mov_b32_e32 v125, v58
	v_mov_b32_e32 v126, v58
	v_mov_b32_e32 v127, v58
	v_mov_b32_e32 v128, v58
	v_mov_b32_e32 v129, v58
	v_mov_b32_e32 v130, v58
	v_mov_b32_e32 v131, v58
	v_mov_b32_e32 v132, v58
	v_mov_b32_e32 v133, v58
	v_mov_b32_e32 v134, v58
	v_mov_b32_e32 v135, v58
	v_mov_b32_e32 v136, v58
	v_mov_b32_e32 v137, v58
	v_mov_b32_e32 v138, v58
	v_mov_b32_e32 v139, v58
	v_mov_b32_e32 v140, v58
	v_mov_b32_e32 v141, v58
	v_mov_b32_e32 v142, v58
	v_mov_b32_e32 v143, v58
	v_mov_b32_e32 v144, v58
	v_mov_b32_e32 v145, v58
	v_mov_b32_e32 v34, v58
	v_mov_b32_e32 v35, v58
	v_mov_b32_e32 v36, v58
	v_mov_b32_e32 v37, v58
	v_mov_b32_e32 v38, v58
	v_mov_b32_e32 v39, v58
	v_mov_b32_e32 v40, v58
	v_mov_b32_e32 v41, v58
	v_mov_b32_e32 v42, v58
	v_mov_b32_e32 v43, v58
	v_mov_b32_e32 v44, v58
	v_mov_b32_e32 v45, v58
	v_mov_b32_e32 v46, v58
	v_mov_b32_e32 v47, v58
	v_mov_b32_e32 v48, v58
	v_mov_b32_e32 v49, v58
	v_mov_b32_e32 v50, v58
	v_mov_b32_e32 v51, v58
	v_mov_b32_e32 v52, v58
	v_mov_b32_e32 v53, v58
	v_mov_b32_e32 v54, v58
	v_mov_b32_e32 v55, v58
	v_mov_b32_e32 v56, v58
	v_mov_b32_e32 v57, v58
	v_mov_b32_e32 v66, v58
	v_mov_b32_e32 v67, v58
	v_mov_b32_e32 v68, v58
	v_mov_b32_e32 v69, v58
	v_mov_b32_e32 v70, v58
	v_mov_b32_e32 v71, v58
	v_mov_b32_e32 v72, v58
	v_mov_b32_e32 v73, v58
	.p2align	6

.LBB0_972:
	s_ashr_i32 s19, s18, 31
	s_lshl_b64 s[2:3], s[18:19], 19
	s_add_u32 s20, s38, s2
	s_addc_u32 s21, s39, s3
	s_and_b64 s[2:3], s[6:7], exec
	s_cselect_b32 s2, s21, s29
	s_cselect_b32 s3, s20, s28
	s_ashr_i32 s17, s16, 31
	s_lshl_b64 s[22:23], s[16:17], 19
	s_add_u32 s22, s40, s22
	s_addc_u32 s23, s41, s23
	s_and_b64 s[34:35], s[6:7], exec
	s_cselect_b32 s17, s23, s31
	s_cselect_b32 s19, s22, s30
	s_add_u32 s28, s28, 0x40080
	s_addc_u32 s29, s29, 0
	s_add_u32 s25, s30, 0x100
	v_mov_b32_e32 v2, 0
	s_addc_u32 s27, s31, 0
	s_mov_b32 s50, -2
	v_mov_b32_e32 v3, v2
	v_mov_b32_e32 v4, v2
	v_mov_b32_e32 v5, v2
	v_mov_b32_e32 v6, v2
	v_mov_b32_e32 v7, v2
	v_mov_b32_e32 v8, v2
	v_mov_b32_e32 v9, v2
	v_mov_b32_e32 v18, v2
	v_mov_b32_e32 v19, v2
	v_mov_b32_e32 v20, v2
	v_mov_b32_e32 v21, v2
	v_mov_b32_e32 v22, v2
	v_mov_b32_e32 v23, v2
	v_mov_b32_e32 v24, v2
	v_mov_b32_e32 v25, v2
	v_mov_b32_e32 v34, v2
	v_mov_b32_e32 v35, v2
	v_mov_b32_e32 v36, v2
	v_mov_b32_e32 v37, v2
	v_mov_b32_e32 v38, v2
	v_mov_b32_e32 v39, v2
	v_mov_b32_e32 v40, v2
	v_mov_b32_e32 v41, v2
	v_mov_b32_e32 v50, v2
	v_mov_b32_e32 v51, v2
	v_mov_b32_e32 v52, v2
	v_mov_b32_e32 v53, v2
	v_mov_b32_e32 v54, v2
	v_mov_b32_e32 v55, v2
	v_mov_b32_e32 v56, v2
	v_mov_b32_e32 v57, v2
	v_mov_b32_e32 v10, v2
	v_mov_b32_e32 v11, v2
	v_mov_b32_e32 v12, v2
	v_mov_b32_e32 v13, v2
	v_mov_b32_e32 v14, v2
	v_mov_b32_e32 v15, v2
	v_mov_b32_e32 v16, v2
	v_mov_b32_e32 v17, v2
	v_mov_b32_e32 v26, v2
	v_mov_b32_e32 v27, v2
	v_mov_b32_e32 v28, v2
	v_mov_b32_e32 v29, v2
	v_mov_b32_e32 v30, v2
	v_mov_b32_e32 v31, v2
	v_mov_b32_e32 v32, v2
	v_mov_b32_e32 v33, v2
	v_mov_b32_e32 v42, v2
	v_mov_b32_e32 v43, v2
	v_mov_b32_e32 v44, v2
	v_mov_b32_e32 v45, v2
	v_mov_b32_e32 v46, v2
	v_mov_b32_e32 v47, v2
	v_mov_b32_e32 v48, v2
	v_mov_b32_e32 v49, v2
	v_mov_b32_e32 v58, v2
	v_mov_b32_e32 v59, v2
	v_mov_b32_e32 v60, v2
	v_mov_b32_e32 v61, v2
	v_mov_b32_e32 v62, v2
	v_mov_b32_e32 v63, v2
	v_mov_b32_e32 v64, v2
	v_mov_b32_e32 v65, v2
	v_mov_b32_e32 v66, v2
	v_mov_b32_e32 v67, v2
	v_mov_b32_e32 v68, v2
	v_mov_b32_e32 v69, v2
	v_mov_b32_e32 v70, v2
	v_mov_b32_e32 v71, v2
	v_mov_b32_e32 v72, v2
	v_mov_b32_e32 v73, v2
	v_mov_b32_e32 v82, v2
	v_mov_b32_e32 v83, v2
	v_mov_b32_e32 v84, v2
	v_mov_b32_e32 v85, v2
	v_mov_b32_e32 v86, v2
	v_mov_b32_e32 v87, v2
	v_mov_b32_e32 v88, v2
	v_mov_b32_e32 v89, v2
	v_mov_b32_e32 v98, v2
	v_mov_b32_e32 v99, v2
	v_mov_b32_e32 v100, v2
	v_mov_b32_e32 v101, v2
	v_mov_b32_e32 v102, v2
	v_mov_b32_e32 v103, v2
	v_mov_b32_e32 v104, v2
	v_mov_b32_e32 v105, v2
	v_mov_b32_e32 v114, v2
	v_mov_b32_e32 v115, v2
	v_mov_b32_e32 v116, v2
	v_mov_b32_e32 v117, v2
	v_mov_b32_e32 v118, v2
	v_mov_b32_e32 v119, v2
	v_mov_b32_e32 v120, v2
	v_mov_b32_e32 v121, v2
	v_mov_b32_e32 v74, v2
	v_mov_b32_e32 v75, v2
	v_mov_b32_e32 v76, v2
	v_mov_b32_e32 v77, v2
	v_mov_b32_e32 v78, v2
	v_mov_b32_e32 v79, v2
	v_mov_b32_e32 v80, v2
	v_mov_b32_e32 v81, v2
	v_mov_b32_e32 v90, v2
	v_mov_b32_e32 v91, v2
	v_mov_b32_e32 v92, v2
	v_mov_b32_e32 v93, v2
	v_mov_b32_e32 v94, v2
	v_mov_b32_e32 v95, v2
	v_mov_b32_e32 v96, v2
	v_mov_b32_e32 v97, v2
	v_mov_b32_e32 v106, v2
	v_mov_b32_e32 v107, v2
	v_mov_b32_e32 v108, v2
	v_mov_b32_e32 v109, v2
	v_mov_b32_e32 v110, v2
	v_mov_b32_e32 v111, v2
	v_mov_b32_e32 v112, v2
	v_mov_b32_e32 v113, v2
	v_mov_b32_e32 v122, v2
	v_mov_b32_e32 v123, v2
	v_mov_b32_e32 v124, v2
	v_mov_b32_e32 v125, v2
	v_mov_b32_e32 v126, v2
	v_mov_b32_e32 v127, v2
	v_mov_b32_e32 v128, v2
	v_mov_b32_e32 v129, v2
	.p2align	6

.LBB0_1096:
	s_ashr_i32 s19, s18, 31
	s_lshl_b64 s[20:21], s[18:19], 19
	s_add_u32 s20, s39, s20
	s_addc_u32 s21, s40, s21
	s_and_b64 s[22:23], s[4:5], exec
	s_cselect_b32 s19, s21, s27
	s_cselect_b32 s25, s20, s26
	s_ashr_i32 s17, s16, 31
	s_lshl_b64 s[22:23], s[16:17], 19
	s_add_u32 s22, s36, s22
	s_addc_u32 s23, s37, s23
	s_and_b64 s[30:31], s[4:5], exec
	s_cselect_b32 s17, s23, s29
	s_cselect_b32 s53, s22, s28
	s_add_u32 s26, s26, 0x40080
	s_addc_u32 s27, s27, 0
	s_add_u32 s56, s28, 0x100
	v_mov_b32_e32 v2, 0
	s_addc_u32 s57, s29, 0
	s_mov_b32 s58, -2
	v_mov_b32_e32 v3, v2
	v_mov_b32_e32 v4, v2
	v_mov_b32_e32 v5, v2
	v_mov_b32_e32 v10, v2
	v_mov_b32_e32 v11, v2
	v_mov_b32_e32 v12, v2
	v_mov_b32_e32 v13, v2
	v_mov_b32_e32 v18, v2
	v_mov_b32_e32 v19, v2
	v_mov_b32_e32 v20, v2
	v_mov_b32_e32 v21, v2
	v_mov_b32_e32 v26, v2
	v_mov_b32_e32 v27, v2
	v_mov_b32_e32 v28, v2
	v_mov_b32_e32 v29, v2
	v_mov_b32_e32 v34, v2
	v_mov_b32_e32 v35, v2
	v_mov_b32_e32 v36, v2
	v_mov_b32_e32 v37, v2
	v_mov_b32_e32 v42, v2
	v_mov_b32_e32 v43, v2
	v_mov_b32_e32 v44, v2
	v_mov_b32_e32 v45, v2
	v_mov_b32_e32 v50, v2
	v_mov_b32_e32 v51, v2
	v_mov_b32_e32 v52, v2
	v_mov_b32_e32 v53, v2
	v_mov_b32_e32 v58, v2
	v_mov_b32_e32 v59, v2
	v_mov_b32_e32 v60, v2
	v_mov_b32_e32 v61, v2
	v_mov_b32_e32 v6, v2
	v_mov_b32_e32 v7, v2
	v_mov_b32_e32 v8, v2
	v_mov_b32_e32 v9, v2
	v_mov_b32_e32 v14, v2
	v_mov_b32_e32 v15, v2
	v_mov_b32_e32 v16, v2
	v_mov_b32_e32 v17, v2
	v_mov_b32_e32 v22, v2
	v_mov_b32_e32 v23, v2
	v_mov_b32_e32 v24, v2
	v_mov_b32_e32 v25, v2
	v_mov_b32_e32 v30, v2
	v_mov_b32_e32 v31, v2
	v_mov_b32_e32 v32, v2
	v_mov_b32_e32 v33, v2
	v_mov_b32_e32 v38, v2
	v_mov_b32_e32 v39, v2
	v_mov_b32_e32 v40, v2
	v_mov_b32_e32 v41, v2
	v_mov_b32_e32 v46, v2
	v_mov_b32_e32 v47, v2
	v_mov_b32_e32 v48, v2
	v_mov_b32_e32 v49, v2
	v_mov_b32_e32 v54, v2
	v_mov_b32_e32 v55, v2
	v_mov_b32_e32 v56, v2
	v_mov_b32_e32 v57, v2
	v_mov_b32_e32 v62, v2
	v_mov_b32_e32 v63, v2
	v_mov_b32_e32 v64, v2
	v_mov_b32_e32 v65, v2
	v_mov_b32_e32 v66, v2
	v_mov_b32_e32 v67, v2
	v_mov_b32_e32 v68, v2
	v_mov_b32_e32 v69, v2
	v_mov_b32_e32 v74, v2
	v_mov_b32_e32 v75, v2
	v_mov_b32_e32 v76, v2
	v_mov_b32_e32 v77, v2
	v_mov_b32_e32 v82, v2
	v_mov_b32_e32 v83, v2
	v_mov_b32_e32 v84, v2
	v_mov_b32_e32 v85, v2
	v_mov_b32_e32 v90, v2
	v_mov_b32_e32 v91, v2
	v_mov_b32_e32 v92, v2
	v_mov_b32_e32 v93, v2
	v_mov_b32_e32 v98, v2
	v_mov_b32_e32 v99, v2
	v_mov_b32_e32 v100, v2
	v_mov_b32_e32 v101, v2
	v_mov_b32_e32 v106, v2
	v_mov_b32_e32 v107, v2
	v_mov_b32_e32 v108, v2
	v_mov_b32_e32 v109, v2
	v_mov_b32_e32 v114, v2
	v_mov_b32_e32 v115, v2
	v_mov_b32_e32 v116, v2
	v_mov_b32_e32 v117, v2
	v_mov_b32_e32 v122, v2
	v_mov_b32_e32 v123, v2
	v_mov_b32_e32 v124, v2
	v_mov_b32_e32 v125, v2
	v_mov_b32_e32 v70, v2
	v_mov_b32_e32 v71, v2
	v_mov_b32_e32 v72, v2
	v_mov_b32_e32 v73, v2
	v_mov_b32_e32 v78, v2
	v_mov_b32_e32 v79, v2
	v_mov_b32_e32 v80, v2
	v_mov_b32_e32 v81, v2
	v_mov_b32_e32 v86, v2
	v_mov_b32_e32 v87, v2
	v_mov_b32_e32 v88, v2
	v_mov_b32_e32 v89, v2
	v_mov_b32_e32 v94, v2
	v_mov_b32_e32 v95, v2
	v_mov_b32_e32 v96, v2
	v_mov_b32_e32 v97, v2
	v_mov_b32_e32 v102, v2
	v_mov_b32_e32 v103, v2
	v_mov_b32_e32 v104, v2
	v_mov_b32_e32 v105, v2
	v_mov_b32_e32 v110, v2
	v_mov_b32_e32 v111, v2
	v_mov_b32_e32 v112, v2
	v_mov_b32_e32 v113, v2
	v_mov_b32_e32 v118, v2
	v_mov_b32_e32 v119, v2
	v_mov_b32_e32 v120, v2
	v_mov_b32_e32 v121, v2
	v_mov_b32_e32 v126, v2
	v_mov_b32_e32 v127, v2
	v_mov_b32_e32 v128, v2
	v_mov_b32_e32 v129, v2
	.p2align	6

.LBB0_1196:
	s_add_u32 s2, s34, 0x100
	v_mov_b32_e32 v2, 0
	s_addc_u32 s3, s35, 0
	s_mov_b32 s29, -2
	v_mov_b32_e32 v3, v2
	v_mov_b32_e32 v4, v2
	v_mov_b32_e32 v5, v2
	v_mov_b32_e32 v6, v2
	v_mov_b32_e32 v7, v2
	v_mov_b32_e32 v8, v2
	v_mov_b32_e32 v9, v2
	v_mov_b32_e32 v18, v2
	v_mov_b32_e32 v19, v2
	v_mov_b32_e32 v20, v2
	v_mov_b32_e32 v21, v2
	v_mov_b32_e32 v22, v2
	v_mov_b32_e32 v23, v2
	v_mov_b32_e32 v24, v2
	v_mov_b32_e32 v25, v2
	v_mov_b32_e32 v34, v2
	v_mov_b32_e32 v35, v2
	v_mov_b32_e32 v36, v2
	v_mov_b32_e32 v37, v2
	v_mov_b32_e32 v38, v2
	v_mov_b32_e32 v39, v2
	v_mov_b32_e32 v40, v2
	v_mov_b32_e32 v41, v2
	v_mov_b32_e32 v50, v2
	v_mov_b32_e32 v51, v2
	v_mov_b32_e32 v52, v2
	v_mov_b32_e32 v53, v2
	v_mov_b32_e32 v54, v2
	v_mov_b32_e32 v55, v2
	v_mov_b32_e32 v56, v2
	v_mov_b32_e32 v57, v2
	v_mov_b32_e32 v10, v2
	v_mov_b32_e32 v11, v2
	v_mov_b32_e32 v12, v2
	v_mov_b32_e32 v13, v2
	v_mov_b32_e32 v14, v2
	v_mov_b32_e32 v15, v2
	v_mov_b32_e32 v16, v2
	v_mov_b32_e32 v17, v2
	v_mov_b32_e32 v26, v2
	v_mov_b32_e32 v27, v2
	v_mov_b32_e32 v28, v2
	v_mov_b32_e32 v29, v2
	v_mov_b32_e32 v30, v2
	v_mov_b32_e32 v31, v2
	v_mov_b32_e32 v32, v2
	v_mov_b32_e32 v33, v2
	v_mov_b32_e32 v42, v2
	v_mov_b32_e32 v43, v2
	v_mov_b32_e32 v44, v2
	v_mov_b32_e32 v45, v2
	v_mov_b32_e32 v46, v2
	v_mov_b32_e32 v47, v2
	v_mov_b32_e32 v48, v2
	v_mov_b32_e32 v49, v2
	v_mov_b32_e32 v58, v2
	v_mov_b32_e32 v59, v2
	v_mov_b32_e32 v60, v2
	v_mov_b32_e32 v61, v2
	v_mov_b32_e32 v62, v2
	v_mov_b32_e32 v63, v2
	v_mov_b32_e32 v64, v2
	v_mov_b32_e32 v65, v2
	v_mov_b32_e32 v66, v2
	v_mov_b32_e32 v67, v2
	v_mov_b32_e32 v68, v2
	v_mov_b32_e32 v69, v2
	v_mov_b32_e32 v70, v2
	v_mov_b32_e32 v71, v2
	v_mov_b32_e32 v72, v2
	v_mov_b32_e32 v73, v2
	v_mov_b32_e32 v82, v2
	v_mov_b32_e32 v83, v2
	v_mov_b32_e32 v84, v2
	v_mov_b32_e32 v85, v2
	v_mov_b32_e32 v86, v2
	v_mov_b32_e32 v87, v2
	v_mov_b32_e32 v88, v2
	v_mov_b32_e32 v89, v2
	v_mov_b32_e32 v98, v2
	v_mov_b32_e32 v99, v2
	v_mov_b32_e32 v100, v2
	v_mov_b32_e32 v101, v2
	v_mov_b32_e32 v102, v2
	v_mov_b32_e32 v103, v2
	v_mov_b32_e32 v104, v2
	v_mov_b32_e32 v105, v2
	v_mov_b32_e32 v114, v2
	v_mov_b32_e32 v115, v2
	v_mov_b32_e32 v116, v2
	v_mov_b32_e32 v117, v2
	v_mov_b32_e32 v118, v2
	v_mov_b32_e32 v119, v2
	v_mov_b32_e32 v120, v2
	v_mov_b32_e32 v121, v2
	v_mov_b32_e32 v74, v2
	v_mov_b32_e32 v75, v2
	v_mov_b32_e32 v76, v2
	v_mov_b32_e32 v77, v2
	v_mov_b32_e32 v78, v2
	v_mov_b32_e32 v79, v2
	v_mov_b32_e32 v80, v2
	v_mov_b32_e32 v81, v2
	v_mov_b32_e32 v90, v2
	v_mov_b32_e32 v91, v2
	v_mov_b32_e32 v92, v2
	v_mov_b32_e32 v93, v2
	v_mov_b32_e32 v94, v2
	v_mov_b32_e32 v95, v2
	v_mov_b32_e32 v96, v2
	v_mov_b32_e32 v97, v2
	v_mov_b32_e32 v106, v2
	v_mov_b32_e32 v107, v2
	v_mov_b32_e32 v108, v2
	v_mov_b32_e32 v109, v2
	v_mov_b32_e32 v110, v2
	v_mov_b32_e32 v111, v2
	v_mov_b32_e32 v112, v2
	v_mov_b32_e32 v113, v2
	v_mov_b32_e32 v122, v2
	v_mov_b32_e32 v123, v2
	v_mov_b32_e32 v124, v2
	v_mov_b32_e32 v125, v2
	v_mov_b32_e32 v126, v2
	v_mov_b32_e32 v127, v2
	v_mov_b32_e32 v128, v2
	v_mov_b32_e32 v129, v2
	.p2align	6
